# NSA: K/V prefetch addresses via scalar row/column offset + 32-bit v_add (SGPR-base loads) instead of 64-bit VALU mad/adds
# speedup vs baseline: 1.0020x; 1.0020x over previous
; DI float sigmoidf_(float x) { return __builtin_amdgcn_rcpf(1.0f + __expf(-x)); }
; DI void fs_reset(FState& st) { st.o0 = f16zero(); st.o1 = f16zero(); st.m = NINF; st.l = 0.f; }
; #define NSA_LOADT(it_, KR, VR) do { const int i_ = (it_); if (i_ < ntot) { const bool s_ = i_ < nsel; const int j_ = s_ ? i_ : c - (i_ - nsel); const bf16_t* p_ = sbase + (size_t)(64 * j_) * NZ; \
;         KR = *(const u32x4*)(p_ + (s_ ? ZC_KS : ZC_KW)); VR = *(const u32x4*)(p_ + (s_ ? ZC_VS : ZC_VW)); } } while (0)
; DI void nsa_task(LAS unsigned char* lds, const bf16_t* Z, const unsigned* selm, const bf16_t* OCMP, bf16_t* YA, int b, int hk, int c, int tid, int wave, int lane) {
;     ...
;     const float g_cmp = sigmoidf_(bf2f(zr[ZC_GA + head])), g_slc = sigmoidf_(bf2f(zr[ZC_GA + 8 + head])), g_win = sigmoidf_(bf2f(zr[ZC_GA + 16 + head]));
;     f32x16 y0 = f16zero(), y1 = f16zero();
;     FState st; fs_reset(st);
;     const int nsel = EN_SLC ? c + 1 : 0, nwin = EN_WIN ? (c + 1 < 9 ? c + 1 : 9) : 0, ntot = nsel + nwin;
;     const int skey = tid >> 3, sch = tid & 7;
;     const int kdst = skey * 128 + ((sch ^ ((skey >> 1) & 7)) << 4), vdst = 8192 + skey * 128 + ((sch * 16) ^ (((skey >> 1) & 1) << 6));
;     const bf16_t* sbase = Z + ((size_t)b * SEQ + skey) * NZ + hk * 64 + sch * 8;
;     u32x4 kA = {0u, 0u, 0u, 0u}, vA = kA, kB = kA, vB = kA, kC = kA, vC = kA;
;     ...
;     NSA_LOADT(0, kA, vA); NSA_LOADT(1, kB, vB); NSA_LOADT(2, kC, vC);
;     for (int it0 = 0; it0 < ntot; it0 += 3) {
;         NSA_STEP(it0, kA, vA);
;         if (it0 + 1 < ntot) NSA_STEP(it0 + 1, kB, vB);
;         if (it0 + 2 < ntot) NSA_STEP(it0 + 2, kC, vC);
;     }
.LBB0_740:
	s_waitcnt vmcnt(3)
	v_lshlrev_b32_e32 v5, 16, v5
	v_mul_f32_e32 v5, 0xbfb8aa3b, v5
	v_exp_f32_e32 v5, v5
	v_lshlrev_b32_e32 v195, 6, v4
	v_lshlrev_b32_e32 v4, 7, v194
	v_lshlrev_b32_e32 v6, 4, v205
	v_add_f32_e32 v5, 1.0, v5
	v_rcp_f32_e32 v197, v5
	v_lshlrev_b32_e32 v5, 6, v206
	v_and_b32_e32 v5, 64, v5
	v_mov_b32_e32 v16, v3
	v_mov_b32_e32 v17, v3
	v_and_or_b32 v205, v6, s66, v4
	v_lshlrev_b32_e32 v206, 4, v207
	v_lshlrev_b32_e32 v207, 4, v208
	v_lshlrev_b32_e32 v208, 4, v209
	v_lshlrev_b32_e32 v209, 4, v212
	s_add_i32 s4, s50, s69
	v_bitop3_b32 v212, v5, v4, v2 bitop3:0xde
	v_mov_b32_e32 v2, v3
	v_mov_b32_e32 v4, v3
	v_mov_b32_e32 v5, v3
	v_mov_b32_e32 v6, v3
	v_mov_b32_e32 v7, v3
	v_mov_b32_e32 v8, v3
	v_mov_b32_e32 v9, v3
	v_mov_b32_e32 v10, v3
	v_mov_b32_e32 v11, v3
	v_mov_b32_e32 v12, v3
	v_mov_b32_e32 v13, v3
	v_mov_b32_e32 v14, v3
	v_mov_b32_e32 v15, v3
	v_mov_b64_e32 v[80:81], v[16:17]
	v_mov_b64_e32 v[64:65], v[16:17]
	v_mov_b64_e32 v[48:49], v[16:17]
	v_mov_b64_e32 v[32:33], v[16:17]
	v_lshlrev_b32_e32 v194, 2, v210
	v_add_u32_e32 v210, 0xfffffe00, v190
	v_lshlrev_b32_e32 v211, 7, v211
	s_add_i32 s52, s4, -5
	s_mov_b32 s53, 0
	v_sub_u32_e32 v213, 0, v202
	s_sub_i32 s70, 0, s69
	s_add_i32 s71, s69, -2
	s_add_i32 s72, s69, -1
	v_mov_b32_e32 v214, 0
	v_mov_b32_e32 v216, 0xff800000
	s_mov_b32 s74, 0
	v_mov_b64_e32 v[78:79], v[14:15]
	v_mov_b64_e32 v[76:77], v[12:13]
	v_mov_b64_e32 v[74:75], v[10:11]
	v_mov_b64_e32 v[72:73], v[8:9]
	v_mov_b64_e32 v[70:71], v[6:7]
	v_mov_b64_e32 v[68:69], v[4:5]
	v_mov_b64_e32 v[66:67], v[2:3]
	v_mov_b64_e32 v[62:63], v[14:15]
	v_mov_b64_e32 v[60:61], v[12:13]
	v_mov_b64_e32 v[58:59], v[10:11]
	v_mov_b64_e32 v[56:57], v[8:9]
	v_mov_b64_e32 v[54:55], v[6:7]
	v_mov_b64_e32 v[52:53], v[4:5]
	v_mov_b64_e32 v[50:51], v[2:3]
	v_mov_b64_e32 v[46:47], v[14:15]
	v_mov_b64_e32 v[44:45], v[12:13]
	v_mov_b64_e32 v[42:43], v[10:11]
	v_mov_b64_e32 v[40:41], v[8:9]
	v_mov_b64_e32 v[38:39], v[6:7]
	v_mov_b64_e32 v[36:37], v[4:5]
	v_mov_b64_e32 v[34:35], v[2:3]
	v_mov_b64_e32 v[30:31], v[14:15]
	v_mov_b64_e32 v[28:29], v[12:13]
	v_mov_b64_e32 v[26:27], v[10:11]
	v_mov_b64_e32 v[24:25], v[8:9]
	v_mov_b64_e32 v[22:23], v[6:7]
	v_mov_b64_e32 v[20:21], v[4:5]
	v_mov_b64_e32 v[18:19], v[2:3]
	v_readfirstlane_b32 s98, v192
	v_readfirstlane_b32 s99, v193
	v_subrev_u32_e32 v219, s98, v192
	v_and_b32_e32 v5, 64, v198
	v_xor_b32_e32 v4, 32, v198
	v_add_u32_e32 v5, 64, v5
	v_cmp_lt_i32_e32 vcc, v4, v5
	v_cndmask_b32_e32 v4, v198, v4, vcc
	v_lshlrev_b32_e32 v215, 2, v4
	v_add3_u32 v217, v211, v203, v204
	v_add_u32_e32 v218, v217, v202
	v_add_u32_e32 v217, v217, v213
	ds_write_b128 v205, v[162:165]
	ds_write_b128 v212, v[166:169] offset:8192
	v_add_u32_e32 v221, v201, v206
	v_add_u32_e32 v222, v201, v207
	v_add_u32_e32 v223, v201, v208
	v_add_u32_e32 v224, v201, v209
	s_waitcnt lgkmcnt(0)
	s_barrier
	ds_read_b128 v[226:229], v221
	ds_read_b128 v[230:233], v221 offset:4096
	ds_read_b128 v[234:237], v222
	ds_read_b128 v[238:241], v222 offset:4096
	s_waitcnt lgkmcnt(3)
	v_mfma_f32_32x32x16_bf16 v[98:113], v[226:229], v[146:149], 0
	s_waitcnt lgkmcnt(2)
	v_mfma_f32_32x32x16_bf16 v[82:97], v[230:233], v[146:149], 0
	ds_read_b128 v[226:229], v223
	ds_read_b128 v[230:233], v223 offset:4096
	s_waitcnt lgkmcnt(3)
	v_mfma_f32_32x32x16_bf16 v[98:113], v[234:237], v[150:153], v[98:113]
	s_waitcnt lgkmcnt(2)
	v_mfma_f32_32x32x16_bf16 v[82:97], v[238:241], v[150:153], v[82:97]
	ds_read_b128 v[234:237], v224
	ds_read_b128 v[238:241], v224 offset:4096
	s_waitcnt lgkmcnt(3)
	v_mfma_f32_32x32x16_bf16 v[98:113], v[226:229], v[154:157], v[98:113]
	s_waitcnt lgkmcnt(2)
	v_mfma_f32_32x32x16_bf16 v[82:97], v[230:233], v[154:157], v[82:97]
	s_waitcnt lgkmcnt(1)
	v_mfma_f32_32x32x16_bf16 v[98:113], v[234:237], v[158:161], v[98:113]
	s_waitcnt lgkmcnt(0)
	v_mfma_f32_32x32x16_bf16 v[82:97], v[238:241], v[158:161], v[82:97]
.LBB0_741:
	s_mov_b32 s76, 0
	s_add_i32 s73, s74, 3
	s_cmp_ge_u32 s73, s51
	s_cselect_b64 s[6:7], -1, 0
	s_waitcnt vmcnt(1)
	ds_write_b128 v205, v[170:173] offset:16384
	s_waitcnt vmcnt(0)
	ds_write_b128 v212, v[174:177] offset:24576
	s_waitcnt lgkmcnt(0)
	s_barrier
	s_cmp_lg_u32 s74, 0
	s_cbranch_scc1 .Lnsp_not3
	s_and_b64 vcc, exec, s[6:7]
	s_cbranch_vccnz .Lnsp_not3
	s_cmp_gt_u32 s73, s69
	s_cselect_b64 s[4:5], -1, 0
	s_add_i32 s8, s52, 2
	s_and_b64 s[4:5], s[4:5], exec
	s_cselect_b32 s8, s8, s73
	s_cselect_b32 s16, 0x1000, s65
	s_cselect_b32 s4, s64, 0x500
	s_lshl_b32 s8, s8, 6
	s_mov_b32 s5, s17
	s_mul_i32 s8, s8, 0x2200
	s_add_i32 s4, s4, s8
	s_add_i32 s16, s16, s8
	v_add_u32_e32 v6, s4, v219
	v_add_u32_e32 v4, s16, v219
	global_load_dwordx4 v[162:165], v6, s[98:99]
	global_load_dwordx4 v[166:169], v4, s[98:99]
.Lnsp_not3:
	s_add_i32 s4, s74, 4
	s_cmp_ge_u32 s4, s51
	s_cbranch_scc1 .LBB0_743
	s_cmp_gt_u32 s4, s69
	s_cselect_b64 s[8:9], -1, 0
	s_add_i32 s5, s52, 1
	s_and_b64 s[8:9], s[8:9], exec
	s_cselect_b32 s4, s5, s4
	s_cselect_b32 s16, 0x1000, s65
	s_cselect_b32 s8, s64, 0x500
	s_lshl_b32 s4, s4, 6
	s_mov_b32 s9, s17
	s_mul_i32 s4, s4, 0x2200
	s_add_i32 s8, s8, s4
	s_add_i32 s16, s16, s4
	v_add_u32_e32 v6, s8, v219
	v_add_u32_e32 v4, s16, v219
	global_load_dwordx4 v[170:173], v6, s[98:99]
	global_load_dwordx4 v[174:177], v4, s[98:99]

; #define LAS __attribute__((address_space(3)))
; #define MFMA32(a, b, c) __builtin_amdgcn_mfma_f32_32x32x16_bf16((a), (b), (c), 0, 0, 0)
; DI float fexp2(float x) { return __builtin_amdgcn_exp2f(x); }
; DI s16x4 vtr(const LAS unsigned char* p) { return __builtin_bit_cast(s16x4, __builtin_amdgcn_ds_read_tr16_b64_v4i16((LAS v4i16_t*)p)); }
; DI void flash_pv(FState& st, f32x16& p0, f32x16& p1, bool rowon, const LAS unsigned char* vb, int lane) {
;     ...
;     const float cl = rowon ? SM_C : 0.0f;
;     const float bl = rowon ? ((st.m == NINF) ? 0.0f : -st.m * SM_C) : NINF;
;     float sum = 0.f;
; #pragma unroll
;     for (int r = 0; r < 16; ++r) { p0[r] = fexp2(__builtin_fmaf(p0[r], cl, bl)); p1[r] = fexp2(__builtin_fmaf(p1[r], cl, bl)); sum += p0[r] + p1[r]; }
;     st.l += sum;
;     const int h = lane >> 5;
;     const int vx = (((lane & 15) >> 3) & 1) * 64;
;     const LAS unsigned char* vp = vb + (4 * h + ((lane & 15) >> 2)) * 128 + ((lane >> 4) & 1) * 32 + (lane & 3) * 8;
; #pragma unroll
;     for (int sub = 0; sub < 2; ++sub)
; #pragma unroll
;         for (int s2 = 0; s2 < 2; ++s2) {
;             const bf16x8 pf = pack8h(sub ? p1 : p0, s2);
;             const LAS unsigned char* vq = vp + (32 * sub + 16 * s2) * 128;
;             { const s16x4 lo = vtr(vq + vx), hi = vtr(vq + 1024 + vx); const bf16x8 vf = {lo[0], lo[1], lo[2], lo[3], hi[0], hi[1], hi[2], hi[3]}; st.o0 = MFMA32(vf, pf, st.o0); }
;             { const s16x4 lo = vtr(vq + (64 - vx)), hi = vtr(vq + 1024 + (64 - vx)); const bf16x8 vf = {lo[0], lo[1], lo[2], lo[3], hi[0], hi[1], hi[2], hi[3]}; st.o1 = MFMA32(vf, pf, st.o1); }
;         }
.LBB0_759:
	s_or_b64 exec, exec, s[4:5]
	v_fma_f32 v2, v98, v5, v4
	v_exp_f32_e32 v12, v2
	v_fma_f32 v2, v82, v5, v4
	v_exp_f32_e32 v246, v2
	s_waitcnt lgkmcnt(3)
	v_mfma_f32_32x32x16_bf16 v[130:145], v[226:229], v[154:157], v[130:145]
	v_fma_f32 v2, v99, v5, v4
	v_exp_f32_e32 v6, v2
	v_fma_f32 v2, v83, v5, v4
	v_exp_f32_e32 v2, v2
	v_add_f32_e32 v7, v12, v246
	s_add_i32 s77, s74, 1
	s_cmp_ge_u32 s77, s51
	v_pk_add_f32 v[8:9], v[6:7], v[2:3]
	v_fma_f32 v7, v100, v5, v4
	v_add_f32_e32 v99, v8, v9
	s_waitcnt lgkmcnt(2)
	v_mfma_f32_32x32x16_bf16 v[114:129], v[230:233], v[154:157], v[114:129]
	v_fma_f32 v8, v84, v5, v4
	v_exp_f32_e32 v7, v7
	v_exp_f32_e32 v247, v8
	v_fma_f32 v8, v101, v5, v4
	v_fma_f32 v9, v85, v5, v4
	v_exp_f32_e32 v8, v8
	v_exp_f32_e32 v98, v9
	v_add_f32_e32 v9, v7, v247
	v_cvt_pk_bf16_f32 v6, v12, v6
	v_cvt_pk_bf16_f32 v7, v7, v8
	s_waitcnt lgkmcnt(1)
	v_mfma_f32_32x32x16_bf16 v[130:145], v[234:237], v[158:161], v[130:145]
	v_pk_add_f32 v[10:11], v[8:9], v[98:99]
	v_fma_f32 v9, v102, v5, v4
	v_add_f32_e32 v101, v10, v11
	v_fma_f32 v10, v86, v5, v4
	v_exp_f32_e32 v99, v10
	v_fma_f32 v10, v103, v5, v4
	v_exp_f32_e32 v9, v9
	v_exp_f32_e32 v14, v10
	v_fma_f32 v10, v87, v5, v4
	v_exp_f32_e32 v100, v10
	s_waitcnt lgkmcnt(0)
	v_mfma_f32_32x32x16_bf16 v[114:129], v[238:241], v[158:161], v[114:129]
	v_add_f32_e32 v15, v9, v99
	v_cvt_pk_bf16_f32 v8, v9, v14
	v_pk_add_f32 v[10:11], v[14:15], v[100:101]
	s_nop 0
	v_add_f32_e32 v87, v10, v11
	v_fma_f32 v10, v104, v5, v4
	v_exp_f32_e32 v15, v10
	v_fma_f32 v10, v88, v5, v4
	v_exp_f32_e32 v101, v10
	v_fma_f32 v10, v105, v5, v4
	v_exp_f32_e32 v16, v10
	v_fma_f32 v10, v89, v5, v4
	v_exp_f32_e32 v86, v10
	v_add_f32_e32 v17, v15, v101
	v_cvt_pk_bf16_f32 v9, v15, v16
	v_pk_add_f32 v[10:11], v[16:17], v[86:87]
	s_nop 0
	v_add_f32_e32 v89, v10, v11
	v_fma_f32 v10, v106, v5, v4
	v_exp_f32_e32 v87, v10
	v_fma_f32 v10, v90, v5, v4
	v_exp_f32_e32 v248, v10
	v_fma_f32 v10, v107, v5, v4
	v_exp_f32_e32 v90, v10
	v_fma_f32 v10, v91, v5, v4
	v_exp_f32_e32 v88, v10
	v_fma_f32 v10, v108, v5, v4
	v_exp_f32_e32 v107, v10
	v_fma_f32 v10, v92, v5, v4
	v_add_f32_e32 v91, v87, v248
	v_exp_f32_e32 v108, v10
	v_pk_add_f32 v[10:11], v[90:91], v[88:89]
	v_fma_f32 v91, v112, v5, v4
	v_add_f32_e32 v103, v10, v11
	v_fma_f32 v10, v109, v5, v4
	v_exp_f32_e32 v104, v10
	v_fma_f32 v10, v93, v5, v4
	v_exp_f32_e32 v102, v10
	ds_read_b64_tr_b16 v[10:11], v218 offset:8192
	ds_read_b64_tr_b16 v[12:13], v218 offset:9216
	ds_read_b64_tr_b16 v[14:15], v217 offset:8256
	ds_read_b64_tr_b16 v[16:17], v217 offset:9280
	ds_read_b64_tr_b16 v[82:83], v218 offset:10240
	ds_read_b64_tr_b16 v[84:85], v218 offset:11264
	s_waitcnt lgkmcnt(4)
	v_mfma_f32_32x32x16_bf16 v[66:81], v[10:13], v[6:9], v[66:81]
	v_fma_f32 v10, v110, v5, v4
	v_exp_f32_e32 v89, v10
	v_fma_f32 v10, v111, v5, v4
	v_exp_f32_e32 v92, v10
	v_exp_f32_e32 v109, v91
	v_add_f32_e32 v105, v107, v108
	ds_read_b64_tr_b16 v[10:11], v217 offset:10304
	ds_read_b64_tr_b16 v[12:13], v217 offset:11328
	s_waitcnt lgkmcnt(4)
	v_mfma_f32_32x32x16_bf16 v[50:65], v[14:17], v[6:9], v[50:65]
	v_fma_f32 v6, v113, v5, v4
	v_exp_f32_e32 v106, v6
	v_cvt_pk_bf16_f32 v6, v87, v90
	v_cvt_pk_bf16_f32 v7, v107, v104
	v_cvt_pk_bf16_f32 v8, v89, v92
	v_cvt_pk_bf16_f32 v9, v109, v106
	v_pk_add_f32 v[14:15], v[104:105], v[102:103]
	s_waitcnt lgkmcnt(2)
	v_mfma_f32_32x32x16_bf16 v[66:81], v[82:85], v[6:9], v[66:81]
	v_add_f32_e64 v91, v14, v15
	v_fma_f32 v14, v94, v5, v4
	v_exp_f32_e32 v94, v14
	ds_read_b64_tr_b16 v[14:15], v218 offset:12288
	ds_read_b64_tr_b16 v[16:17], v218 offset:13312
	v_fma_f32 v82, v95, v5, v4
	v_exp_f32_e32 v90, v82
	v_add_f32_e32 v93, v89, v94
	s_waitcnt lgkmcnt(2)
	v_mfma_f32_32x32x16_bf16 v[50:65], v[10:13], v[6:9], v[50:65]
	v_cvt_pk_bf16_f32 v6, v246, v2
	v_cvt_pk_bf16_f32 v7, v247, v98
	v_cvt_pk_bf16_f32 v8, v99, v100
	v_cvt_pk_bf16_f32 v9, v101, v86
	ds_read_b64_tr_b16 v[10:11], v218 offset:14336
	ds_read_b64_tr_b16 v[12:13], v218 offset:15360
	v_pk_add_f32 v[82:83], v[92:93], v[90:91]
	v_fma_f32 v2, v96, v5, v4
	s_waitcnt lgkmcnt(2)
	v_mfma_f32_32x32x16_bf16 v[66:81], v[14:17], v[6:9], v[66:81]
	ds_read_b64_tr_b16 v[14:15], v217 offset:12352
	ds_read_b64_tr_b16 v[16:17], v217 offset:13376
	v_add_f32_e64 v87, v82, v83
	v_fmac_f32_e32 v4, v97, v5
	ds_read_b64_tr_b16 v[82:83], v217 offset:14400
	ds_read_b64_tr_b16 v[84:85], v217 offset:15424
	v_exp_f32_e32 v2, v2
	v_exp_f32_e32 v86, v4
	v_cvt_pk_bf16_f32 v4, v248, v88
	s_waitcnt lgkmcnt(2)
	v_mfma_f32_32x32x16_bf16 v[50:65], v[14:17], v[6:9], v[50:65]
	v_cvt_pk_bf16_f32 v5, v108, v102
	v_cvt_pk_bf16_f32 v6, v94, v90
	v_cvt_pk_bf16_f32 v7, v2, v86
	v_add_f32_e32 v107, v109, v2
	v_add_f32_e64 v8, v106, v86
	v_add_f32_e64 v9, v107, v87
	v_add_f32_e32 v2, v8, v9
	v_mfma_f32_32x32x16_bf16 v[66:81], v[10:13], v[4:7], v[66:81]
	v_add_f32_e32 v214, v214, v2
	s_waitcnt lgkmcnt(0)
	v_mfma_f32_32x32x16_bf16 v[50:65], v[82:85], v[4:7], v[50:65]
	s_cbranch_scc1 .LBB0_780
	s_movk_i32 s76, 0x4000
	s_add_i32 s4, s74, 5
	s_cmp_ge_u32 s4, s51
	s_waitcnt vmcnt(1)
	ds_write_b128 v205, v[182:185] offset:32768
	s_waitcnt vmcnt(0)
	ds_write_b128 v212, v[178:181] offset:40960
	s_waitcnt lgkmcnt(0)
	s_barrier
	s_cbranch_scc1 .LBB0_762
	s_cmp_gt_u32 s4, s69
	s_cselect_b64 s[8:9], -1, 0
	s_mov_b32 s5, s52
	s_and_b64 s[8:9], s[8:9], exec
	s_cselect_b32 s4, s5, s4
	s_cselect_b32 s16, 0x1000, s65
	s_cselect_b32 s8, s64, 0x500
	s_lshl_b32 s4, s4, 6
	s_mov_b32 s9, s17
	s_mul_i32 s4, s4, 0x2200
	s_add_i32 s8, s8, s4
	s_add_i32 s16, s16, s4
	v_add_u32_e32 v6, s8, v219
	v_add_u32_e32 v4, s16, v219
	global_load_dwordx4 v[182:185], v6, s[98:99]
	global_load_dwordx4 v[178:181], v4, s[98:99]

.LBB0_781:
	s_add_i32 s4, s74, 6
	s_cmp_ge_u32 s4, s51
	s_waitcnt vmcnt(1)
	ds_write_b128 v205, v[162:165]
	s_waitcnt vmcnt(0)
	ds_write_b128 v212, v[166:169] offset:8192
	s_waitcnt lgkmcnt(0)
	s_barrier
	s_cbranch_scc1 .LBB0_783
	s_cmp_gt_u32 s4, s69
	s_cselect_b64 s[8:9], -1, 0
	s_add_i32 s5, s52, -1
	s_and_b64 s[8:9], s[8:9], exec
	s_cselect_b32 s4, s5, s4
	s_cselect_b32 s16, 0x1000, s65
	s_cselect_b32 s8, s64, 0x500
	s_lshl_b32 s4, s4, 6
	s_mov_b32 s9, s17
	s_mul_i32 s4, s4, 0x2200
	s_add_i32 s8, s8, s4
	s_add_i32 s16, s16, s4
	v_add_u32_e32 v6, s8, v219
	v_add_u32_e32 v4, s16, v219
	global_load_dwordx4 v[162:165], v6, s[98:99]
	global_load_dwordx4 v[166:169], v4, s[98:99]

; #define LAS __attribute__((address_space(3)))
; #define MFMA32(a, b, c) __builtin_amdgcn_mfma_f32_32x32x16_bf16((a), (b), (c), 0, 0, 0)
; DI float fexp2(float x) { return __builtin_amdgcn_exp2f(x); }
; DI s16x4 vtr(const LAS unsigned char* p) { return __builtin_bit_cast(s16x4, __builtin_amdgcn_ds_read_tr16_b64_v4i16((LAS v4i16_t*)p)); }
; DI void flash_pv(FState& st, f32x16& p0, f32x16& p1, bool rowon, const LAS unsigned char* vb, int lane) {
;     ...
;     const float cl = rowon ? SM_C : 0.0f;
;     const float bl = rowon ? ((st.m == NINF) ? 0.0f : -st.m * SM_C) : NINF;
;     float sum = 0.f;
; #pragma unroll
;     for (int r = 0; r < 16; ++r) { p0[r] = fexp2(__builtin_fmaf(p0[r], cl, bl)); p1[r] = fexp2(__builtin_fmaf(p1[r], cl, bl)); sum += p0[r] + p1[r]; }
;     st.l += sum;
;     const int h = lane >> 5;
;     const int vx = (((lane & 15) >> 3) & 1) * 64;
;     const LAS unsigned char* vp = vb + (4 * h + ((lane & 15) >> 2)) * 128 + ((lane >> 4) & 1) * 32 + (lane & 3) * 8;
; #pragma unroll
;     for (int sub = 0; sub < 2; ++sub)
; #pragma unroll
;         for (int s2 = 0; s2 < 2; ++s2) {
;             const bf16x8 pf = pack8h(sub ? p1 : p0, s2);
;             const LAS unsigned char* vq = vp + (32 * sub + 16 * s2) * 128;
;             { const s16x4 lo = vtr(vq + vx), hi = vtr(vq + 1024 + vx); const bf16x8 vf = {lo[0], lo[1], lo[2], lo[3], hi[0], hi[1], hi[2], hi[3]}; st.o0 = MFMA32(vf, pf, st.o0); }
;             { const s16x4 lo = vtr(vq + (64 - vx)), hi = vtr(vq + 1024 + (64 - vx)); const bf16x8 vf = {lo[0], lo[1], lo[2], lo[3], hi[0], hi[1], hi[2], hi[3]}; st.o1 = MFMA32(vf, pf, st.o1); }
;         }
.Lnq_759:
	s_or_b64 exec, exec, s[4:5]
	v_fma_f32 v2, v130, v5, v4
	v_exp_f32_e32 v12, v2
	v_fma_f32 v2, v114, v5, v4
	v_exp_f32_e32 v246, v2
	s_waitcnt lgkmcnt(3)
	v_mfma_f32_32x32x16_bf16 v[98:113], v[226:229], v[154:157], v[98:113]
	v_fma_f32 v2, v131, v5, v4
	v_exp_f32_e32 v6, v2
	v_fma_f32 v2, v115, v5, v4
	v_exp_f32_e32 v2, v2
	v_add_f32_e32 v7, v12, v246
	s_add_i32 s77, s74, 1
	s_cmp_ge_u32 s77, s51
	v_pk_add_f32 v[8:9], v[6:7], v[2:3]
	v_fma_f32 v7, v132, v5, v4
	v_add_f32_e32 v131, v8, v9
	s_waitcnt lgkmcnt(2)
	v_mfma_f32_32x32x16_bf16 v[82:97], v[230:233], v[154:157], v[82:97]
	v_fma_f32 v8, v116, v5, v4
	v_exp_f32_e32 v7, v7
	v_exp_f32_e32 v247, v8
	v_fma_f32 v8, v133, v5, v4
	v_fma_f32 v9, v117, v5, v4
	v_exp_f32_e32 v8, v8
	v_exp_f32_e32 v130, v9
	v_add_f32_e32 v9, v7, v247
	v_cvt_pk_bf16_f32 v6, v12, v6
	v_cvt_pk_bf16_f32 v7, v7, v8
	s_waitcnt lgkmcnt(1)
	v_mfma_f32_32x32x16_bf16 v[98:113], v[234:237], v[158:161], v[98:113]
	v_pk_add_f32 v[10:11], v[8:9], v[130:131]
	v_fma_f32 v9, v134, v5, v4
	v_add_f32_e32 v133, v10, v11
	v_fma_f32 v10, v118, v5, v4
	v_exp_f32_e32 v131, v10
	v_fma_f32 v10, v135, v5, v4
	v_exp_f32_e32 v9, v9
	v_exp_f32_e32 v14, v10
	v_fma_f32 v10, v119, v5, v4
	v_exp_f32_e32 v132, v10
	s_waitcnt lgkmcnt(0)
	v_mfma_f32_32x32x16_bf16 v[82:97], v[238:241], v[158:161], v[82:97]
	v_add_f32_e32 v15, v9, v131
	v_cvt_pk_bf16_f32 v8, v9, v14
	v_pk_add_f32 v[10:11], v[14:15], v[132:133]
	s_nop 0
	v_add_f32_e32 v119, v10, v11
	v_fma_f32 v10, v136, v5, v4
	v_exp_f32_e32 v15, v10
	v_fma_f32 v10, v120, v5, v4
	v_exp_f32_e32 v133, v10
	v_fma_f32 v10, v137, v5, v4
	v_exp_f32_e32 v16, v10
	v_fma_f32 v10, v121, v5, v4
	v_exp_f32_e32 v118, v10
	v_add_f32_e32 v17, v15, v133
	v_cvt_pk_bf16_f32 v9, v15, v16
	v_pk_add_f32 v[10:11], v[16:17], v[118:119]
	s_nop 0
	v_add_f32_e32 v121, v10, v11
	v_fma_f32 v10, v138, v5, v4
	v_exp_f32_e32 v119, v10
	v_fma_f32 v10, v122, v5, v4
	v_exp_f32_e32 v248, v10
	v_fma_f32 v10, v139, v5, v4
	v_exp_f32_e32 v122, v10
	v_fma_f32 v10, v123, v5, v4
	v_exp_f32_e32 v120, v10
	v_fma_f32 v10, v140, v5, v4
	v_exp_f32_e32 v139, v10
	v_fma_f32 v10, v124, v5, v4
	v_add_f32_e32 v123, v119, v248
	v_exp_f32_e32 v140, v10
	v_pk_add_f32 v[10:11], v[122:123], v[120:121]
	v_fma_f32 v123, v144, v5, v4
	v_add_f32_e32 v135, v10, v11
	v_fma_f32 v10, v141, v5, v4
	v_exp_f32_e32 v136, v10
	v_fma_f32 v10, v125, v5, v4
	v_exp_f32_e32 v134, v10
	ds_read_b64_tr_b16 v[10:11], v218 offset:8192
	ds_read_b64_tr_b16 v[12:13], v218 offset:9216
	ds_read_b64_tr_b16 v[14:15], v217 offset:8256
	ds_read_b64_tr_b16 v[16:17], v217 offset:9280
	ds_read_b64_tr_b16 v[114:115], v218 offset:10240
	ds_read_b64_tr_b16 v[116:117], v218 offset:11264
	s_waitcnt lgkmcnt(4)
	v_mfma_f32_32x32x16_bf16 v[66:81], v[10:13], v[6:9], v[66:81]
	v_fma_f32 v10, v142, v5, v4
	v_exp_f32_e32 v121, v10
	v_fma_f32 v10, v143, v5, v4
	v_exp_f32_e32 v124, v10
	v_exp_f32_e32 v141, v123
	v_add_f32_e32 v137, v139, v140
	ds_read_b64_tr_b16 v[10:11], v217 offset:10304
	ds_read_b64_tr_b16 v[12:13], v217 offset:11328
	s_waitcnt lgkmcnt(4)
	v_mfma_f32_32x32x16_bf16 v[50:65], v[14:17], v[6:9], v[50:65]
	v_fma_f32 v6, v145, v5, v4
	v_exp_f32_e32 v138, v6
	v_cvt_pk_bf16_f32 v6, v119, v122
	v_cvt_pk_bf16_f32 v7, v139, v136
	v_cvt_pk_bf16_f32 v8, v121, v124
	v_cvt_pk_bf16_f32 v9, v141, v138
	v_pk_add_f32 v[14:15], v[136:137], v[134:135]
	s_waitcnt lgkmcnt(2)
	v_mfma_f32_32x32x16_bf16 v[66:81], v[114:117], v[6:9], v[66:81]
	v_add_f32_e64 v123, v14, v15
	v_fma_f32 v14, v126, v5, v4
	v_exp_f32_e32 v126, v14
	ds_read_b64_tr_b16 v[14:15], v218 offset:12288
	ds_read_b64_tr_b16 v[16:17], v218 offset:13312
	v_fma_f32 v114, v127, v5, v4
	v_exp_f32_e32 v122, v114
	v_add_f32_e32 v125, v121, v126
	s_waitcnt lgkmcnt(2)
	v_mfma_f32_32x32x16_bf16 v[50:65], v[10:13], v[6:9], v[50:65]
	v_cvt_pk_bf16_f32 v6, v246, v2
	v_cvt_pk_bf16_f32 v7, v247, v130
	v_cvt_pk_bf16_f32 v8, v131, v132
	v_cvt_pk_bf16_f32 v9, v133, v118
	ds_read_b64_tr_b16 v[10:11], v218 offset:14336
	ds_read_b64_tr_b16 v[12:13], v218 offset:15360
	v_pk_add_f32 v[114:115], v[124:125], v[122:123]
	v_fma_f32 v2, v128, v5, v4
	s_waitcnt lgkmcnt(2)
	v_mfma_f32_32x32x16_bf16 v[66:81], v[14:17], v[6:9], v[66:81]
	ds_read_b64_tr_b16 v[14:15], v217 offset:12352
	ds_read_b64_tr_b16 v[16:17], v217 offset:13376
	v_add_f32_e64 v119, v114, v115
	v_fmac_f32_e32 v4, v129, v5
	ds_read_b64_tr_b16 v[114:115], v217 offset:14400
	ds_read_b64_tr_b16 v[116:117], v217 offset:15424
	v_exp_f32_e32 v2, v2
	v_exp_f32_e32 v118, v4
	v_cvt_pk_bf16_f32 v4, v248, v120
	s_waitcnt lgkmcnt(2)
	v_mfma_f32_32x32x16_bf16 v[50:65], v[14:17], v[6:9], v[50:65]
	v_cvt_pk_bf16_f32 v5, v140, v134
	v_cvt_pk_bf16_f32 v6, v126, v122
	v_cvt_pk_bf16_f32 v7, v2, v118
	v_add_f32_e32 v139, v141, v2
	v_add_f32_e64 v8, v138, v118
	v_add_f32_e64 v9, v139, v119
	v_add_f32_e32 v2, v8, v9
	v_mfma_f32_32x32x16_bf16 v[66:81], v[10:13], v[4:7], v[66:81]
	v_add_f32_e32 v214, v214, v2
	s_waitcnt lgkmcnt(0)
	v_mfma_f32_32x32x16_bf16 v[50:65], v[114:117], v[4:7], v[50:65]
	s_cbranch_scc1 .Lnq_780
	s_movk_i32 s76, 0x4000
	s_add_i32 s4, s74, 5
	s_cmp_ge_u32 s4, s51
	s_waitcnt vmcnt(1)
	ds_write_b128 v205, v[182:185] offset:32768
	s_waitcnt vmcnt(0)
	ds_write_b128 v212, v[178:181] offset:40960
	s_waitcnt lgkmcnt(0)
	s_barrier
	s_cbranch_scc1 .Lnq_762
	s_cmp_gt_u32 s4, s69
	s_cselect_b64 s[8:9], -1, 0
	s_mov_b32 s5, s52
	s_and_b64 s[8:9], s[8:9], exec
	s_cselect_b32 s4, s5, s4
	s_cselect_b32 s16, 0x1000, s65
	s_cselect_b32 s8, s64, 0x500
	s_lshl_b32 s4, s4, 6
	s_mov_b32 s9, s17
	s_mul_i32 s4, s4, 0x2200
	s_add_i32 s8, s8, s4
	s_add_i32 s16, s16, s4
	v_add_u32_e32 v6, s8, v219
	v_add_u32_e32 v4, s16, v219
	global_load_dwordx4 v[182:185], v6, s[98:99]
	global_load_dwordx4 v[178:181], v4, s[98:99]
